# ssm_gen (P1 slack instance): parameter-table loads (lam/b/c/log_dt) all issued up front into dead VGPRs, original loads become register moves
# speedup vs baseline: 1.0104x; 1.0056x over previous
; __device__ __forceinline__ void ssm_gen(LAS unsigned char* lds, const Args& a, int layer, int g, int j8) {
;     ...
;     {
;         const int p = tid & 63;
;         float lrv[2], liv[2], dtv[2];
; #pragma unroll
;         for (int dir = 0; dir < 2; ++dir) { lrv[dir] = a.lam_re[((layer * 2 + dir) * 32 + g) * 64 + p]; liv[dir] = a.lam_im[((layer * 2 + dir) * 32 + g) * 64 + p]; dtv[dir] = __expf(a.log_dt[(layer * 2 + dir) * 32 + g]); }
; #pragma unroll 1
;         for (int r = 0; r < 9; ++r) {
;             const int idx = tid + 512 * r;
;             if (idx < 2 * 33 * 64) {
;                 const int dir = idx >= 33 * 64 ? 1 : 0, d = (idx - dir * 33 * 64) >> 6;
;                 const float lr = dir ? lrv[1] : lrv[0], li = dir ? liv[1] : liv[0], dt = dir ? dtv[1] : dtv[0];
;                 const float mag = __expf(lr * dt * (float)d);
;                 double rev = (double)li * (double)dt * 0.15915494309189535 * (double)d; rev -= __builtin_rint(rev);
;                 const float rv = (float)rev;
;                 PW[idx] = (f32x2){mag * __builtin_amdgcn_cosf(rv), mag * __builtin_amdgcn_sinf(rv)};
;             }
;         }
; #pragma unroll
;         for (int r = 0; r < 4; ++r) {
;             const int i = tid + 512 * r, dir = i >> 10, pp = (i >> 4) & 63, h = i & 15;
;             const float lr = a.lam_re[((layer * 2 + dir) * 32 + g) * 64 + pp], li = a.lam_im[((layer * 2 + dir) * 32 + g) * 64 + pp], dt = dir ? dtv[1] : dtv[0];
;             const float mag = __expf(lr * dt);
;             double rev = (double)li * (double)dt * 0.15915494309189535; rev -= __builtin_rint(rev);
;             const float abx = mag * __builtin_amdgcn_cosf((float)rev), aby = mag * __builtin_amdgcn_sinf((float)rev);
;             const float den = lr * lr + li * li;
;             const float zr = ((abx - 1.0f) * lr + aby * li) / den, zi = (aby * lr - (abx - 1.0f) * li) / den;
;             const float br = a.b_re[(((size_t)layer * 32 + g) * 64 + pp) * 16 + h], bi = a.b_im[(((size_t)layer * 32 + g) * 64 + pp) * 16 + h];
;             BB[(dir * 64 + pp) * 16 + h] = (f32x2){zr * br - zi * bi, zr * bi + zi * br};
;             const size_t ci = ((((size_t)layer * 2 + dir) * 32 + g) * 16 + h) * 64 + pp;
;             CT[(dir * 64 + pp) * 16 + h] = (f32x2){a.c_re[ci], a.c_im[ci]};
.Ldt_c_norm:
	v_readlane_b32 s24, v254, 53
	v_readlane_b32 s76, v253, 21
	v_readlane_b32 s77, v253, 22
	v_readlane_b32 s78, v253, 23
	v_readlane_b32 s79, v253, 24
	v_readlane_b32 s12, v253, 25
	v_readlane_b32 s13, v253, 26
	v_readlane_b32 s14, v253, 27
	v_readlane_b32 s15, v253, 28
	v_readlane_b32 s16, v253, 29
	v_readlane_b32 s17, v253, 30
	v_readlane_b32 s18, v253, 31
	v_readlane_b32 s19, v253, 32
	v_readlane_b32 s20, v253, 33
	v_readlane_b32 s21, v253, 34
	s_lshl_b32 s25, s24, 12
	s_lshl_b32 s26, s58, 6
	s_add_i32 s25, s25, s26
	v_and_b32_e32 v141, 63, v12
	v_or_b32_e32 v141, s25, v141
	v_lshlrev_b32_e32 v141, 2, v141
	v_add_u32_e32 v142, 0x2000, v141
	v_mov_b32_e32 v143, 0
	s_lshl_b32 s26, s24, 6
	s_add_i32 s26, s26, s58
	s_lshl_b32 s26, s26, 2
	s_add_u32 s26, s12, s26
	s_addc_u32 s27, s13, 0
	global_load_dword v110, v141, s[76:77]
	global_load_dword v111, v141, s[78:79]
	global_load_dword v112, v143, s[26:27]
	global_load_dword v113, v142, s[76:77]
	global_load_dword v114, v142, s[78:79]
	global_load_dword v115, v143, s[26:27] offset:128
	v_lshrrev_b32_e32 v144, 4, v12
	v_and_b32_e32 v145, 15, v12
	s_lshl_b32 s25, s25, 2
	v_lshl_add_u32 v136, v144, 2, s25
	v_add_u32_e32 v137, 0x2000, v136
	s_lshl_b32 s26, s24, 17
	s_lshl_b32 s27, s58, 12
	s_add_i32 s26, s26, s27
	v_lshlrev_b32_e32 v146, 2, v145
	v_lshl_or_b32 v146, v144, 6, v146
	v_add_u32_e32 v146, s26, v146
	s_lshl_b32 s26, s24, 18
	s_lshl_b32 s27, s58, 12
	s_add_i32 s26, s26, s27
	v_lshl_or_b32 v147, v145, 6, v144
	v_lshl_add_u32 v147, v147, 2, s26
	v_add_u32_e32 v148, 0x20000, v147
	global_load_dword v116, v136, s[76:77]
	global_load_dword v117, v136, s[78:79]
	global_load_dword v118, v146, s[14:15]
	global_load_dword v119, v146, s[16:17]
	global_load_dword v120, v147, s[18:19]
	global_load_dword v121, v147, s[20:21]
	global_load_dword v122, v136, s[76:77] offset:128
	global_load_dword v123, v136, s[78:79] offset:128
	global_load_dword v124, v146, s[14:15] offset:2048
	global_load_dword v125, v146, s[16:17] offset:2048
	global_load_dword v126, v147, s[18:19] offset:128
	global_load_dword v127, v147, s[20:21] offset:128
	global_load_dword v128, v137, s[76:77]
	global_load_dword v129, v137, s[78:79]
	global_load_dword v130, v148, s[18:19]
	global_load_dword v131, v148, s[20:21]
	global_load_dword v132, v137, s[76:77] offset:128
	global_load_dword v133, v137, s[78:79] offset:128
	global_load_dword v134, v148, s[18:19] offset:128
	global_load_dword v135, v148, s[20:21] offset:128
	s_nop 0
	v_cmp_gt_i32_e32 vcc, 16, v12
	s_and_saveexec_b64 s[10:11], vcc
	s_cbranch_execz .LBB0_360
	v_readlane_b32 s8, v254, 53
	s_lshl_b32 s5, s58, 4
	s_lshl_b32 s7, s8, 9
	s_add_i32 s5, s5, s7
	v_add_u32_e32 v0, s5, v12
	v_readlane_b32 s12, v253, 25
	v_ashrrev_i32_e32 v1, 31, v0
	v_readlane_b32 s22, v253, 35
	v_readlane_b32 s23, v253, 36
	v_readlane_b32 s9, v254, 54
	v_readlane_b32 s13, v253, 26
	v_lshl_add_u64 v[0:1], v[0:1], 2, s[22:23]
	global_load_dword v0, v[0:1], off
	v_lshl_add_u32 v1, v12, 2, 0
	v_add_u32_e32 v1, 0x20800, v1
	v_readlane_b32 s14, v253, 27
	v_readlane_b32 s15, v253, 28
	v_readlane_b32 s16, v253, 29
	v_readlane_b32 s17, v253, 30
	v_readlane_b32 s18, v253, 31
	v_readlane_b32 s19, v253, 32
	v_readlane_b32 s20, v253, 33
	v_readlane_b32 s21, v253, 34
	v_readlane_b32 s24, v253, 37
	v_readlane_b32 s25, v253, 38
	v_readlane_b32 s26, v253, 39
	v_readlane_b32 s27, v253, 40
	s_waitcnt vmcnt(0)
	ds_write_b32 v1, v0
.LBB0_360:
	s_or_b64 exec, exec, s[10:11]
	v_readlane_b32 s8, v255, 45
	s_add_i32 s8, s58, s8
	v_readlane_b32 s9, v255, 46
	s_lshl_b32 s5, s8, 6
	v_and_b32_e32 v10, 63, v12
	s_mov_b32 s9, s59
	v_or_b32_e32 v200, s5, v10
	v_readlane_b32 s64, v253, 9
	s_lshl_b64 s[8:9], s[8:9], 2
	v_readlane_b32 s12, v253, 25
	v_lshlrev_b64 v[2:3], 2, v[200:201]
	v_readlane_b32 s76, v253, 21
	v_readlane_b32 s77, v253, 22
	v_readlane_b32 s78, v253, 23
	v_readlane_b32 s79, v253, 24
	v_readlane_b32 s13, v253, 26
	s_add_u32 s8, s12, s8
	v_lshl_add_u64 v[0:1], s[76:77], 0, v[2:3]
	v_lshl_add_u64 v[2:3], s[78:79], 0, v[2:3]
	s_addc_u32 s9, s13, s9
	s_waitcnt vmcnt(0)
	v_mov_b32_e32 v0, v110
	s_nop 0
	v_mov_b32_e32 v1, v111
	s_nop 0
	v_mov_b32_e32 v2, v112
	s_add_i32 s7, s5, 0x800
	v_or_b32_e32 v200, s7, v10
	v_lshlrev_b64 v[4:5], 2, v[200:201]
	v_lshl_add_u64 v[6:7], s[76:77], 0, v[4:5]
	v_lshl_add_u64 v[4:5], s[78:79], 0, v[4:5]
	v_lshlrev_b32_e32 v15, 3, v12
	s_mov_b32 s5, 0
	v_readlane_b32 s14, v253, 27
	v_readlane_b32 s15, v253, 28
	v_readlane_b32 s16, v253, 29
	v_readlane_b32 s17, v253, 30
	v_readlane_b32 s18, v253, 31
	v_readlane_b32 s19, v253, 32
	v_readlane_b32 s20, v253, 33
	v_readlane_b32 s21, v253, 34
	v_readlane_b32 s22, v253, 35
	v_readlane_b32 s23, v253, 36
	v_readlane_b32 s24, v253, 37
	v_readlane_b32 s25, v253, 38
	v_readlane_b32 s26, v253, 39
	v_readlane_b32 s27, v253, 40
	v_readlane_b32 s65, v253, 10
	v_readlane_b32 s66, v253, 11
	v_readlane_b32 s67, v253, 12
	v_readlane_b32 s68, v253, 13
	v_readlane_b32 s69, v253, 14
	v_readlane_b32 s70, v253, 15
	v_readlane_b32 s71, v253, 16
	v_readlane_b32 s72, v253, 17
	v_readlane_b32 s73, v253, 18
	v_readlane_b32 s74, v253, 19
	v_readlane_b32 s75, v253, 20
	s_waitcnt vmcnt(0)
	v_mul_f32_e32 v2, 0x3fb8aa3b, v2
	v_exp_f32_e32 v3, v2
	v_mov_b32_e32 v2, v113
	s_nop 0
	v_mov_b32_e32 v4, v114
	s_nop 0
	v_mov_b32_e32 v5, v115
	s_waitcnt vmcnt(0)
	v_mul_f32_e32 v5, 0x3fb8aa3b, v5
	v_exp_f32_e32 v16, v5
	v_add_u32_e32 v5, 0, v15
	s_branch .LBB0_362

; __device__ __forceinline__ void ssm_gen(LAS unsigned char* lds, const Args& a, int layer, int g, int j8) {
;     ...
;         for (int r = 0; r < 4; ++r) {
;             const int i = tid + 512 * r, dir = i >> 10, pp = (i >> 4) & 63, h = i & 15;
;             const float lr = a.lam_re[((layer * 2 + dir) * 32 + g) * 64 + pp], li = a.lam_im[((layer * 2 + dir) * 32 + g) * 64 + pp], dt = dir ? dtv[1] : dtv[0];
;             const float mag = __expf(lr * dt);
;             double rev = (double)li * (double)dt * 0.15915494309189535; rev -= __builtin_rint(rev);
;             const float abx = mag * __builtin_amdgcn_cosf((float)rev), aby = mag * __builtin_amdgcn_sinf((float)rev);
;             const float den = lr * lr + li * li;
;             const float zr = ((abx - 1.0f) * lr + aby * li) / den, zi = (aby * lr - (abx - 1.0f) * li) / den;
;             const float br = a.b_re[(((size_t)layer * 32 + g) * 64 + pp) * 16 + h], bi = a.b_im[(((size_t)layer * 32 + g) * 64 + pp) * 16 + h];
;             BB[(dir * 64 + pp) * 16 + h] = (f32x2){zr * br - zi * bi, zr * bi + zi * br};
;             const size_t ci = ((((size_t)layer * 2 + dir) * 32 + g) * 16 + h) * 64 + pp;
;             CT[(dir * 64 + pp) * 16 + h] = (f32x2){a.c_re[ci], a.c_im[ci]};
.LBB0_364:
	v_readlane_b32 s14, v254, 53
	v_readlane_b32 s15, v254, 54
	s_mov_b32 s15, s59
	s_lshl_b64 s[8:9], s[14:15], 11
	s_lshl_b64 s[10:11], s[58:59], 6
	s_add_u32 s5, s10, s8
	s_addc_u32 s13, s11, s9
	s_lshl_b32 s7, s14, 12
	s_lshl_b32 s8, s58, 6
	s_add_i32 s7, s8, s7
	v_ashrrev_i32_e32 v6, 10, v12
	v_bfe_u32 v5, v12, 4, 6
	v_lshl_add_u32 v0, v6, 11, s7
	v_or_b32_e32 v0, v0, v5
	v_ashrrev_i32_e32 v1, 31, v0
	v_readlane_b32 s64, v253, 9
	v_lshlrev_b64 v[0:1], 2, v[0:1]
	v_readlane_b32 s76, v253, 21
	v_readlane_b32 s77, v253, 22
	v_readlane_b32 s78, v253, 23
	v_readlane_b32 s79, v253, 24
	v_lshl_add_u64 v[8:9], s[76:77], 0, v[0:1]
	v_mov_b32_e32 v8, v116
	v_lshl_add_u64 v[0:1], s[78:79], 0, v[0:1]
	v_mov_b32_e32 v9, v117
	s_movk_i32 s1, 0x400
	v_cmp_gt_u32_e32 vcc, s1, v12
	s_mov_b32 s28, 0x6dc9c883
	s_mov_b32 s29, 0x3fc45f30
	v_cndmask_b32_e32 v2, v16, v3, vcc
	v_cvt_f64_f32_e32 v[18:19], v2
	s_mov_b32 s8, s14
	v_writelane_b32 v254, s8, 53
	v_and_b32_e32 v11, 15, v12
	v_lshlrev_b32_e32 v14, 2, v11
	v_writelane_b32 v254, s9, 54
	s_lshl_b64 s[8:9], s[14:15], 16
	s_lshl_b64 s[10:11], s[58:59], 10
	s_add_u32 s10, s10, s8
	s_addc_u32 s11, s11, s9
	v_lshlrev_b32_e32 v13, 6, v11
	s_movk_i32 s3, 0xfbff
	v_readlane_b32 s65, v253, 10
	v_readlane_b32 s66, v253, 11
	v_readlane_b32 s67, v253, 12
	v_readlane_b32 s68, v253, 13
	v_readlane_b32 s69, v253, 14
	v_readlane_b32 s70, v253, 15
	v_readlane_b32 s71, v253, 16
	v_readlane_b32 s72, v253, 17
	v_readlane_b32 s73, v253, 18
	v_readlane_b32 s74, v253, 19
	v_readlane_b32 s75, v253, 20
	s_waitcnt vmcnt(1)
	v_mul_f32_e32 v0, v2, v8
	v_mul_f32_e32 v0, 0x3fb8aa3b, v0
	v_exp_f32_e32 v4, v0
	s_waitcnt vmcnt(0)
	v_cvt_f64_f32_e32 v[0:1], v9
	v_mul_f64 v[0:1], v[18:19], v[0:1]
	v_mul_f64 v[18:19], v[0:1], s[28:29]
	v_rndne_f64_e32 v[18:19], v[18:19]
	v_fma_f64 v[0:1], v[0:1], s[28:29], -v[18:19]
	v_cvt_f32_f64_e32 v0, v[0:1]
	v_cos_f32_e32 v1, v0
	v_sin_f32_e32 v0, v0
	v_pk_mul_f32 v[20:21], v[8:9], v[8:9]
	v_fma_f32 v18, v4, v1, -1.0
	v_mul_f32_e32 v19, v4, v0
	v_or_b32_e32 v0, s5, v5
	v_mov_b32_e32 v1, s13
	v_lshlrev_b64 v[22:23], 6, v[0:1]
	v_readlane_b32 s12, v253, 25
	v_or_b32_e32 v22, v22, v14
	v_readlane_b32 s14, v253, 27
	v_readlane_b32 s15, v253, 28
	v_readlane_b32 s16, v253, 29
	v_readlane_b32 s17, v253, 30
	v_lshl_add_u64 v[24:25], s[14:15], 0, v[22:23]
	v_mov_b32_e32 v2, v118
	v_lshl_add_u64 v[22:23], s[16:17], 0, v[22:23]
	v_mov_b32_e32 v4, v119
	v_mov_b32_e32 v0, v9
	v_pk_mul_f32 v[22:23], v[0:1], v[18:19] op_sel:[0,1] op_sel_hi:[0,0]
	v_pk_fma_f32 v[24:25], v[8:9], v[18:19], v[22:23]
	v_pk_fma_f32 v[8:9], v[8:9], v[18:19], v[22:23] op_sel_hi:[0,1,1] neg_lo:[0,0,1] neg_hi:[0,0,1]
	v_pk_add_f32 v[18:19], v[20:21], v[20:21] op_sel:[0,1] op_sel_hi:[0,1]
	v_div_scale_f32 v0, s[8:9], v19, v19, v9
	v_rcp_f32_e32 v7, v0
	v_readlane_b32 s18, v253, 31
	v_readlane_b32 s19, v253, 32
	v_readlane_b32 s20, v253, 33
	v_fma_f32 v8, -v0, v7, 1.0
	v_fmac_f32_e32 v7, v8, v7
	v_div_scale_f32 v8, vcc, v9, v19, v9
	v_mul_f32_e32 v17, v8, v7
	v_fma_f32 v20, -v0, v17, v8
	v_fmac_f32_e32 v17, v20, v7
	v_fma_f32 v0, -v0, v17, v8
	v_div_fmas_f32 v0, v0, v7, v17
	v_div_fixup_f32 v9, v0, v19, v9
	v_div_scale_f32 v0, s[8:9], v18, v18, v24
	v_rcp_f32_e32 v7, v0
	v_readlane_b32 s21, v253, 34
	v_readlane_b32 s13, v253, 26
	v_readlane_b32 s22, v253, 35
	v_fma_f32 v8, -v0, v7, 1.0
	v_fmac_f32_e32 v7, v8, v7
	v_div_scale_f32 v8, vcc, v24, v18, v24
	v_mul_f32_e32 v17, v8, v7
	v_fma_f32 v19, -v0, v17, v8
	v_fmac_f32_e32 v17, v19, v7
	v_fma_f32 v0, -v0, v17, v8
	v_div_fmas_f32 v0, v0, v7, v17
	v_ashrrev_i32_e32 v7, 31, v6
	v_lshlrev_b64 v[6:7], 15, v[6:7]
	v_div_fixup_f32 v8, v0, v18, v24
	v_lshl_add_u64 v[6:7], v[6:7], 0, s[10:11]
	v_or3_b32 v6, v6, v13, v5
	v_lshlrev_b64 v[6:7], 2, v[6:7]
	v_lshl_add_u32 v17, v12, 3, 0
	v_readlane_b32 s23, v253, 36
	v_readlane_b32 s24, v253, 37
	v_readlane_b32 s25, v253, 38
	v_readlane_b32 s26, v253, 39
	v_readlane_b32 s27, v253, 40
	s_waitcnt vmcnt(0)
	v_pk_mul_f32 v[18:19], v[4:5], v[8:9] op_sel_hi:[0,1]
	v_pk_fma_f32 v[20:21], v[2:3], v[8:9], v[18:19] op_sel:[0,0,1] op_sel_hi:[1,1,0] neg_lo:[0,0,1] neg_hi:[0,0,1]
	v_pk_fma_f32 v[8:9], v[2:3], v[8:9], v[18:19] op_sel:[0,0,1] op_sel_hi:[0,1,0]
	v_mov_b32_e32 v21, v9
	v_lshl_add_u64 v[8:9], s[18:19], 0, v[6:7]
	v_lshl_add_u64 v[6:7], s[20:21], 0, v[6:7]
	v_mov_b32_e32 v8, v120
	ds_write_b64 v17, v[20:21] offset:33792
	v_mov_b32_e32 v9, v121
	v_add_u32_e32 v7, 0x200, v12
	v_ashrrev_i32_e32 v6, 10, v7
	v_bfe_u32 v28, v7, 4, 6
	v_lshl_add_u32 v0, v6, 11, s7
	v_cmp_gt_u32_e32 vcc, s1, v7
	s_waitcnt vmcnt(0)
	ds_write_b64 v17, v[8:9] offset:50176
	v_or_b32_e32 v8, v0, v28
	v_ashrrev_i32_e32 v9, 31, v8
	v_lshlrev_b64 v[8:9], 2, v[8:9]
	v_lshl_add_u64 v[18:19], s[76:77], 0, v[8:9]
	v_mov_b32_e32 v18, v122
	v_lshl_add_u64 v[8:9], s[78:79], 0, v[8:9]
	v_mov_b32_e32 v19, v123
	v_cndmask_b32_e32 v0, v16, v3, vcc
	v_cvt_f64_f32_e32 v[20:21], v0
	s_waitcnt vmcnt(1)
	v_mul_f32_e32 v8, v0, v18
	v_mul_f32_e32 v8, 0x3fb8aa3b, v8
	v_exp_f32_e32 v22, v8
	s_waitcnt vmcnt(0)
; __device__ __forceinline__ void ssm_gen(LAS unsigned char* lds, const Args& a, int layer, int g, int j8) {
;     ...
;         for (int r = 0; r < 4; ++r) {
;             const int i = tid + 512 * r, dir = i >> 10, pp = (i >> 4) & 63, h = i & 15;
;             const float lr = a.lam_re[((layer * 2 + dir) * 32 + g) * 64 + pp], li = a.lam_im[((layer * 2 + dir) * 32 + g) * 64 + pp], dt = dir ? dtv[1] : dtv[0];
;             const float mag = __expf(lr * dt);
;             double rev = (double)li * (double)dt * 0.15915494309189535; rev -= __builtin_rint(rev);
;             const float abx = mag * __builtin_amdgcn_cosf((float)rev), aby = mag * __builtin_amdgcn_sinf((float)rev);
;             const float den = lr * lr + li * li;
;             const float zr = ((abx - 1.0f) * lr + aby * li) / den, zi = (aby * lr - (abx - 1.0f) * li) / den;
;             const float br = a.b_re[(((size_t)layer * 32 + g) * 64 + pp) * 16 + h], bi = a.b_im[(((size_t)layer * 32 + g) * 64 + pp) * 16 + h];
;             BB[(dir * 64 + pp) * 16 + h] = (f32x2){zr * br - zi * bi, zr * bi + zi * br};
;             const size_t ci = ((((size_t)layer * 2 + dir) * 32 + g) * 16 + h) * 64 + pp;
;             CT[(dir * 64 + pp) * 16 + h] = (f32x2){a.c_re[ci], a.c_im[ci]};
	v_cvt_f64_f32_e32 v[8:9], v19
	v_mul_f64 v[8:9], v[20:21], v[8:9]
	v_mul_f64 v[20:21], v[8:9], s[28:29]
	v_rndne_f64_e32 v[20:21], v[20:21]
	v_fma_f64 v[8:9], v[8:9], s[28:29], -v[20:21]
	v_cvt_f32_f64_e32 v0, v[8:9]
	v_cos_f32_e32 v8, v0
	v_sin_f32_e32 v0, v0
	v_pk_mul_f32 v[20:21], v[18:19], v[18:19]
	v_fma_f32 v8, v22, v8, -1.0
	v_mul_f32_e32 v9, v22, v0
	v_or_b32_e32 v0, s5, v28
	v_lshlrev_b64 v[22:23], 6, v[0:1]
	v_or_b32_e32 v22, v22, v14
	v_lshl_add_u64 v[24:25], s[14:15], 0, v[22:23]
	v_lshl_add_u64 v[22:23], s[16:17], 0, v[22:23]
	v_mov_b32_e32 v22, v125
	s_nop 0
	v_mov_b32_e32 v0, v124
	v_mov_b32_e32 v24, v19
	v_pk_mul_f32 v[24:25], v[24:25], v[8:9] op_sel:[0,1] op_sel_hi:[0,0]
	v_pk_fma_f32 v[26:27], v[18:19], v[8:9], v[24:25]
	v_pk_fma_f32 v[8:9], v[18:19], v[8:9], v[24:25] op_sel_hi:[0,1,1] neg_lo:[0,0,1] neg_hi:[0,0,1]
	v_pk_add_f32 v[18:19], v[20:21], v[20:21] op_sel:[0,1] op_sel_hi:[0,1]
	v_div_scale_f32 v8, s[8:9], v19, v19, v9
	v_rcp_f32_e32 v20, v8
	s_nop 0
	v_fma_f32 v21, -v8, v20, 1.0
	v_fmac_f32_e32 v20, v21, v20
	v_div_scale_f32 v21, vcc, v9, v19, v9
	v_mul_f32_e32 v23, v21, v20
	v_fma_f32 v24, -v8, v23, v21
	v_fmac_f32_e32 v23, v24, v20
	v_fma_f32 v8, -v8, v23, v21
	v_div_fmas_f32 v8, v8, v20, v23
	v_div_fixup_f32 v9, v8, v19, v9
	v_div_scale_f32 v8, s[8:9], v18, v18, v26
	v_rcp_f32_e32 v19, v8
	s_nop 0
	v_fma_f32 v20, -v8, v19, 1.0
	v_fmac_f32_e32 v19, v20, v19
	v_div_scale_f32 v20, vcc, v26, v18, v26
	v_mul_f32_e32 v21, v20, v19
	v_fma_f32 v23, -v8, v21, v20
	v_fmac_f32_e32 v21, v23, v19
	v_fma_f32 v8, -v8, v21, v20
	v_div_fmas_f32 v8, v8, v19, v21
	v_div_fixup_f32 v8, v8, v18, v26
	v_cmp_lt_u32_e32 vcc, s3, v12
	s_waitcnt vmcnt(1)
	v_pk_mul_f32 v[18:19], v[22:23], v[8:9] op_sel:[0,1] op_sel_hi:[0,0]
	s_waitcnt vmcnt(0)
	v_pk_fma_f32 v[20:21], v[0:1], v[8:9], v[18:19] neg_lo:[0,0,1] neg_hi:[0,0,1]
	v_pk_fma_f32 v[8:9], v[0:1], v[8:9], v[18:19] op_sel_hi:[0,1,1]
	v_and_b32_e32 v0, 0x1ffffc00, v7
	v_lshlrev_b32_e32 v7, 4, v28
	v_or3_b32 v0, v7, v0, v11
	v_ashrrev_i32_e32 v7, 31, v6
	v_lshlrev_b64 v[6:7], 15, v[6:7]
	v_lshl_add_u64 v[6:7], v[6:7], 0, s[10:11]
	v_or3_b32 v6, v6, v13, v28
	v_lshlrev_b64 v[6:7], 2, v[6:7]
	v_mov_b32_e32 v21, v9
	v_lshl_add_u64 v[8:9], s[18:19], 0, v[6:7]
	v_lshl_add_u64 v[6:7], s[20:21], 0, v[6:7]
	v_mov_b32_e32 v8, v126
	v_lshl_add_u32 v0, v0, 3, 0
	v_mov_b32_e32 v9, v127
	s_waitcnt vmcnt(0)
	ds_write2st64_b64 v0, v[20:21], v[8:9] offset0:66 offset1:98
	v_add_u32_e32 v0, 0x400, v12
	v_ashrrev_i32_e32 v6, 10, v0
	v_lshl_add_u32 v0, v6, 11, s7
	v_or_b32_e32 v8, v0, v5
	v_ashrrev_i32_e32 v9, 31, v8
	v_lshlrev_b64 v[18:19], 2, v[8:9]
	v_lshl_add_u64 v[8:9], s[76:77], 0, v[18:19]
	v_lshl_add_u64 v[18:19], s[78:79], 0, v[18:19]
	v_mov_b32_e32 v8, v128
	v_cndmask_b32_e32 v0, v16, v3, vcc
	v_mov_b32_e32 v9, v129
	v_cvt_f64_f32_e32 v[20:21], v0
	s_waitcnt vmcnt(1)
	v_mul_f32_e32 v7, v0, v8
	v_mul_f32_e32 v7, 0x3fb8aa3b, v7
	s_waitcnt vmcnt(0)
	v_cvt_f64_f32_e32 v[18:19], v9
	v_mul_f64 v[18:19], v[20:21], v[18:19]
	v_mul_f64 v[20:21], v[18:19], s[28:29]
	v_rndne_f64_e32 v[20:21], v[20:21]
	v_fma_f64 v[18:19], v[18:19], s[28:29], -v[20:21]
	v_cvt_f32_f64_e32 v0, v[18:19]
	v_exp_f32_e32 v7, v7
	v_cos_f32_e32 v18, v0
	v_sin_f32_e32 v0, v0
	v_pk_mul_f32 v[20:21], v[8:9], v[8:9]
	v_fma_f32 v18, v7, v18, -1.0
	v_mul_f32_e32 v19, v7, v0
	v_mov_b32_e32 v0, v9
	v_pk_mul_f32 v[22:23], v[0:1], v[18:19] op_sel:[0,1] op_sel_hi:[0,0]
	v_pk_fma_f32 v[24:25], v[8:9], v[18:19], v[22:23]
	v_pk_fma_f32 v[8:9], v[8:9], v[18:19], v[22:23] op_sel_hi:[0,1,1] neg_lo:[0,0,1] neg_hi:[0,0,1]
	v_pk_add_f32 v[18:19], v[20:21], v[20:21] op_sel:[0,1] op_sel_hi:[0,1]
	v_div_scale_f32 v0, s[8:9], v19, v19, v9
	v_rcp_f32_e32 v7, v0
	v_add_u32_e32 v22, 0x600, v12
	v_bfe_u32 v23, v22, 4, 6
	v_fma_f32 v8, -v0, v7, 1.0
	v_fmac_f32_e32 v7, v8, v7
	v_div_scale_f32 v8, vcc, v9, v19, v9
	v_mul_f32_e32 v20, v8, v7
	v_fma_f32 v21, -v0, v20, v8
	v_fmac_f32_e32 v20, v21, v7
	v_fma_f32 v0, -v0, v20, v8
	v_div_fmas_f32 v0, v0, v7, v20
	v_div_fixup_f32 v9, v0, v19, v9
	v_div_scale_f32 v0, s[8:9], v18, v18, v24
	v_rcp_f32_e32 v7, v0
	s_nop 0
	v_fma_f32 v8, -v0, v7, 1.0
	v_fmac_f32_e32 v7, v8, v7
	v_div_scale_f32 v8, vcc, v24, v18, v24
	v_mul_f32_e32 v19, v8, v7
	v_fma_f32 v20, -v0, v19, v8
	v_fmac_f32_e32 v19, v20, v7
	v_fma_f32 v0, -v0, v19, v8
	v_div_fmas_f32 v0, v0, v7, v19
	v_ashrrev_i32_e32 v7, 31, v6
	v_lshlrev_b64 v[6:7], 15, v[6:7]
	v_lshl_add_u64 v[6:7], v[6:7], 0, s[10:11]
	v_div_fixup_f32 v8, v0, v18, v24
	v_or3_b32 v6, v6, v13, v5
	v_pk_mul_f32 v[18:19], v[4:5], v[8:9] op_sel_hi:[0,1]
	v_lshlrev_b64 v[4:5], 2, v[6:7]
	v_lshl_add_u64 v[6:7], s[18:19], 0, v[4:5]
	v_lshl_add_u64 v[4:5], s[20:21], 0, v[4:5]
	v_mov_b32_e32 v6, v130
	v_pk_fma_f32 v[20:21], v[2:3], v[8:9], v[18:19] op_sel:[0,0,1] op_sel_hi:[1,1,0] neg_lo:[0,0,1] neg_hi:[0,0,1]
	v_mov_b32_e32 v7, v131
	v_pk_fma_f32 v[8:9], v[2:3], v[8:9], v[18:19] op_sel:[0,0,1] op_sel_hi:[0,1,0]
	v_ashrrev_i32_e32 v2, 10, v22
	v_lshl_add_u32 v0, v2, 11, s7
	v_or_b32_e32 v4, v0, v23
	v_ashrrev_i32_e32 v5, 31, v4
	v_cmp_gt_u32_e32 vcc, s1, v22
	v_mov_b32_e32 v21, v9
	ds_write_b64 v17, v[20:21] offset:41984
	v_cndmask_b32_e32 v0, v16, v3, vcc
	v_cvt_f64_f32_e32 v[8:9], v0
	s_waitcnt vmcnt(0)
; __device__ __forceinline__ void ssm_gen(LAS unsigned char* lds, const Args& a, int layer, int g, int j8) {
;     ...
;         for (int r = 0; r < 4; ++r) {
;             const int i = tid + 512 * r, dir = i >> 10, pp = (i >> 4) & 63, h = i & 15;
;             const float lr = a.lam_re[((layer * 2 + dir) * 32 + g) * 64 + pp], li = a.lam_im[((layer * 2 + dir) * 32 + g) * 64 + pp], dt = dir ? dtv[1] : dtv[0];
;             const float mag = __expf(lr * dt);
;             double rev = (double)li * (double)dt * 0.15915494309189535; rev -= __builtin_rint(rev);
;             const float abx = mag * __builtin_amdgcn_cosf((float)rev), aby = mag * __builtin_amdgcn_sinf((float)rev);
;             const float den = lr * lr + li * li;
;             const float zr = ((abx - 1.0f) * lr + aby * li) / den, zi = (aby * lr - (abx - 1.0f) * li) / den;
;             const float br = a.b_re[(((size_t)layer * 32 + g) * 64 + pp) * 16 + h], bi = a.b_im[(((size_t)layer * 32 + g) * 64 + pp) * 16 + h];
;             BB[(dir * 64 + pp) * 16 + h] = (f32x2){zr * br - zi * bi, zr * bi + zi * br};
;             const size_t ci = ((((size_t)layer * 2 + dir) * 32 + g) * 16 + h) * 64 + pp;
;             CT[(dir * 64 + pp) * 16 + h] = (f32x2){a.c_re[ci], a.c_im[ci]};
;         }
;     }
;     __syncthreads();
;     if (j8 == 0 && tid < 128) APOW[tid] = PW[((tid >> 6) * 33 + 32) * 64 + (tid & 63)];
	ds_write_b64 v17, v[6:7] offset:58368
	v_lshlrev_b64 v[6:7], 2, v[4:5]
	v_lshl_add_u64 v[4:5], s[76:77], 0, v[6:7]
	v_lshl_add_u64 v[6:7], s[78:79], 0, v[6:7]
	v_mov_b32_e32 v4, v132
	s_waitcnt vmcnt(0)
	v_mul_f32_e32 v3, v0, v4
	v_mov_b32_e32 v5, v133
	v_mul_f32_e32 v3, 0x3fb8aa3b, v3
	v_exp_f32_e32 v3, v3
	s_waitcnt vmcnt(0)
	v_cvt_f64_f32_e32 v[6:7], v5
	v_mul_f64 v[6:7], v[8:9], v[6:7]
	v_mul_f64 v[8:9], v[6:7], s[28:29]
	v_rndne_f64_e32 v[8:9], v[8:9]
	v_fma_f64 v[6:7], v[6:7], s[28:29], -v[8:9]
	v_cvt_f32_f64_e32 v0, v[6:7]
	v_cos_f32_e32 v6, v0
	v_sin_f32_e32 v0, v0
	v_mov_b32_e32 v18, v5
	v_pk_mul_f32 v[8:9], v[4:5], v[4:5]
	v_fma_f32 v6, v3, v6, -1.0
	v_mul_f32_e32 v7, v3, v0
	v_or_b32_e32 v0, s5, v23
	v_lshlrev_b64 v[0:1], 6, v[0:1]
	v_or_b32_e32 v0, v0, v14
	v_lshl_add_u64 v[16:17], s[14:15], 0, v[0:1]
	v_lshl_add_u64 v[0:1], s[16:17], 0, v[0:1]
	v_mov_b32_e32 v0, v125
	v_pk_mul_f32 v[18:19], v[18:19], v[6:7] op_sel:[0,1] op_sel_hi:[0,0]
	v_mov_b32_e32 v16, v124
	v_pk_fma_f32 v[20:21], v[4:5], v[6:7], v[18:19]
	v_pk_fma_f32 v[4:5], v[4:5], v[6:7], v[18:19] op_sel_hi:[0,1,1] neg_lo:[0,0,1] neg_hi:[0,0,1]
	v_pk_add_f32 v[6:7], v[8:9], v[8:9] op_sel:[0,1] op_sel_hi:[0,1]
	v_div_scale_f32 v1, s[8:9], v7, v7, v5
	v_rcp_f32_e32 v3, v1
	s_nop 0
	v_fma_f32 v4, -v1, v3, 1.0
	v_fmac_f32_e32 v3, v4, v3
	v_div_scale_f32 v4, vcc, v5, v7, v5
	v_mul_f32_e32 v8, v4, v3
	v_fma_f32 v9, -v1, v8, v4
	v_fmac_f32_e32 v8, v9, v3
	v_fma_f32 v1, -v1, v8, v4
	v_div_fmas_f32 v1, v1, v3, v8
	v_div_fixup_f32 v5, v1, v7, v5
	v_div_scale_f32 v1, s[8:9], v6, v6, v20
	v_rcp_f32_e32 v3, v1
	s_nop 0
	v_fma_f32 v4, -v1, v3, 1.0
	v_fmac_f32_e32 v3, v4, v3
	v_div_scale_f32 v4, vcc, v20, v6, v20
	v_mul_f32_e32 v7, v4, v3
	v_fma_f32 v8, -v1, v7, v4
	v_fmac_f32_e32 v7, v8, v3
	v_fma_f32 v1, -v1, v7, v4
	v_div_fmas_f32 v1, v1, v3, v7
	v_div_fixup_f32 v4, v1, v6, v20
	v_and_b32_e32 v3, 0x1ffffc00, v22
	v_cmp_gt_i32_e32 vcc, s87, v12
	s_and_b64 s[8:9], s[46:47], vcc
	s_waitcnt vmcnt(1)
	v_pk_mul_f32 v[6:7], v[0:1], v[4:5] op_sel:[0,1] op_sel_hi:[0,0]
	s_waitcnt vmcnt(0)
	v_pk_fma_f32 v[0:1], v[16:17], v[4:5], v[6:7] neg_lo:[0,0,1] neg_hi:[0,0,1]
	v_pk_fma_f32 v[4:5], v[16:17], v[4:5], v[6:7] op_sel_hi:[0,1,1]
	v_lshlrev_b32_e32 v4, 4, v23
	v_or3_b32 v3, v4, v3, v11
	v_lshl_add_u32 v6, v3, 3, 0
	v_ashrrev_i32_e32 v3, 31, v2
	v_lshlrev_b64 v[2:3], 15, v[2:3]
	v_lshl_add_u64 v[2:3], v[2:3], 0, s[10:11]
	v_or3_b32 v2, v2, v13, v23
	v_mov_b32_e32 v1, v5
	v_lshlrev_b64 v[4:5], 2, v[2:3]
	v_lshl_add_u64 v[2:3], s[18:19], 0, v[4:5]
	v_lshl_add_u64 v[4:5], s[20:21], 0, v[4:5]
	v_mov_b32_e32 v2, v134
	s_nop 0
	v_mov_b32_e32 v3, v135
	s_waitcnt vmcnt(0)
	ds_write2st64_b64 v6, v[0:1], v[2:3] offset0:66 offset1:98
	s_waitcnt lgkmcnt(0)
	s_barrier
	s_and_saveexec_b64 s[10:11], s[8:9]
	s_cbranch_execz .LBB0_366
	v_lshrrev_b32_e32 v0, 6, v12
	s_movk_i32 s1, 0x4200
	s_lshl_b32 s5, s86, 3
	v_readlane_b32 s8, v254, 37
	v_mul_lo_u32 v0, v0, s1
	v_lshlrev_b32_e32 v1, 3, v10
	v_readlane_b32 s9, v254, 38
	s_add_u32 s5, s8, s5
	v_add3_u32 v0, 0, v0, v1
	s_addc_u32 s7, s9, 0
	s_lshl_b32 s8, s58, 7
	s_mov_b32 s9, s59
	ds_read_b64 v[0:1], v0 offset:16384
	s_lshl_b64 s[8:9], s[8:9], 3
	s_add_u32 s8, s5, s8
	s_addc_u32 s9, s7, s9
	v_ashrrev_i32_e32 v13, 31, v12
	v_lshl_add_u64 v[2:3], v[12:13], 3, s[8:9]
	s_waitcnt lgkmcnt(0)
	global_store_dwordx2 v[2:3], v[0:1], off
